# in-projection q/k epilogue: packed bf16 results staged per head block in a wave-private LDS tile and written back as full 128-byte row segments with dwordx4 stores (was row-per-lane 8-byte stores)
# baseline (speedup 1.0000x reference)
.LBB0_957:
	v_mul_f32_e32 v133, v115, v115
	v_fmac_f32_e32 v133, v114, v114
	v_fmac_f32_e32 v133, v116, v116
	v_fmac_f32_e32 v133, v117, v117
	v_fmac_f32_e32 v133, v118, v118
	v_fmac_f32_e32 v133, v119, v119
	v_fmac_f32_e32 v133, v120, v120
	v_fmac_f32_e32 v133, v121, v121
	v_fmac_f32_e32 v133, v122, v122
	v_fmac_f32_e32 v133, v123, v123
	v_fmac_f32_e32 v133, v124, v124
	v_fmac_f32_e32 v133, v125, v125
	v_fmac_f32_e32 v133, v126, v126
	v_fmac_f32_e32 v133, v127, v127
	v_fmac_f32_e32 v133, v128, v128
	v_fmac_f32_e32 v133, v129, v129
	v_fmac_f32_e32 v133, v82, v82
	v_fmac_f32_e32 v133, v83, v83
	v_fmac_f32_e32 v133, v84, v84
	v_fmac_f32_e32 v133, v85, v85
	v_fmac_f32_e32 v133, v86, v86
	v_fmac_f32_e32 v133, v87, v87
	v_pk_mul_f32 v[146:147], v[88:89], v[88:89]
	v_pk_mul_f32 v[144:145], v[90:91], v[90:91]
	v_add_f32_e32 v133, v146, v133
	v_add_f32_e32 v133, v147, v133
	v_add_f32_e32 v133, v144, v133
	v_and_b32_e32 v131, 64, v195
	v_pk_mul_f32 v[142:143], v[92:93], v[92:93]
	v_add_f32_e32 v133, v145, v133
	v_xor_b32_e32 v130, 32, v195
	v_add_u32_e32 v131, 64, v131
	v_add_f32_e32 v133, v142, v133
	v_cmp_lt_i32_e32 vcc, v130, v131
	v_pk_mul_f32 v[140:141], v[94:95], v[94:95]
	v_add_f32_e32 v133, v143, v133
	v_cndmask_b32_e32 v130, v195, v130, vcc
	v_add_f32_e32 v133, v140, v133
	v_lshlrev_b32_e32 v135, 2, v130
	v_pk_mul_f32 v[130:131], v[96:97], v[96:97]
	v_add_f32_e32 v133, v141, v133
	v_add_f32_e32 v130, v130, v133
	v_add_f32_e32 v130, v131, v130
	ds_bpermute_b32 v131, v135, v130
	v_lshlrev_b32_e32 v138, 4, v132
	v_lshlrev_b32_e32 v156, 2, v132
	s_cmp_eq_u32 s37, 2
	s_cselect_b64 s[0:1], -1, 0
	s_waitcnt lgkmcnt(0)
	v_add_f32_e32 v130, v130, v131
	v_fmamk_f32 v137, v130, 0x3c800000, v188
	v_and_b32_e32 v249, 63, v184
	v_lshlrev_b32_e32 v250, 2, v249
	global_load_dword v251, v250, s[28:29]
	v_lshrrev_b32_e32 v242, 6, v184
	v_lshlrev_b32_e32 v231, 8, v242
	v_add_u32_e32 v231, 0x11c00, v231
	v_add_u32_e32 v253, v231, v250
	v_add_u32_e32 v231, v231, v138
	s_waitcnt vmcnt(0)
	ds_write_b32 v253, v251
	v_mul_u32_u24_e32 v242, 0x1200, v242
	v_add_u32_e32 v242, 0xc010, v242
	v_and_b32_e32 v250, 31, v249
	v_lshrrev_b32_e32 v251, 5, v249
	v_mul_u32_u24_e32 v250, 144, v250
	v_lshl_add_u32 v250, v251, 3, v250
	v_add_u32_e32 v253, v242, v250
	v_lshrrev_b32_e32 v250, 3, v249
	v_and_b32_e32 v251, 7, v249
	v_lshlrev_b32_e32 v251, 4, v251
	v_mul_u32_u24_e32 v249, 144, v250
	v_add3_u32 v249, v249, v251, v242
	v_lshl_add_u32 v251, v250, 10, v251
	v_mov_b32_e32 v250, v249
	v_mov_b32_e32 v249, v253
	s_waitcnt lgkmcnt(0)
	ds_read_b128 v[130:133], v231
	s_cmp_lt_i32 s36, 64
	s_cselect_b64 s[36:37], -1, 0
	s_and_b64 s[0:1], s[36:37], s[0:1]
	s_mov_b32 s4, 0x800000
	v_or_b32_e32 v140, v136, v156
	s_mov_b64 s[38:39], -1
	v_cmp_gt_f32_e64 s[36:37], s4, v137
	s_and_b64 vcc, exec, s[0:1]
	v_ashrrev_i32_e32 v141, 31, v140
	s_cbranch_vccnz .LBB0_959
	s_mov_b64 s[38:39], 0

.LBB0_961:
	s_xor_b64 s[38:39], s[0:1], -1
	v_mov_b32_e32 v139, v0
	v_lshl_add_u64 v[138:139], s[28:29], 0, v[138:139]
	s_add_u32 s28, s68, s34
	s_addc_u32 s29, s69, s35
	v_lshlrev_b64 v[142:143], 10, v[170:171]
	v_lshl_add_u64 v[174:175], s[28:29], 0, v[142:143]
	v_pk_mul_f32 v[130:131], s[22:23], v[130:131] op_sel_hi:[0,1]
	v_pk_mul_f32 v[132:133], s[22:23], v[132:133] op_sel_hi:[0,1]
	v_cvt_pk_bf16_f32 v130, v130, v131
	v_cvt_pk_bf16_f32 v131, v132, v133
	v_lshl_add_u64 v[132:133], v[140:141], 1, v[174:175]
	s_nop 1
	v_readfirstlane_b32 s100, v132
	v_readfirstlane_b32 s101, v133
	ds_write_b64 v249, v[130:131]
	ds_read_b128 v[130:133], v231 offset:32
	v_or_b32_e32 v158, 8, v156
	v_or_b32_e32 v142, v136, v158
	v_cndmask_b32_e64 v137, 0, 1, s[38:39]
	s_mov_b64 s[34:35], -1
	v_cmp_ne_u32_e64 s[36:37], 1, v137
	s_andn2_b64 vcc, exec, s[38:39]
	v_ashrrev_i32_e32 v143, 31, v142
	s_cbranch_vccnz .LBB0_963
	s_mov_b64 s[34:35], 0

.LBB0_965:
	s_mov_b32 s23, s22
	s_nop 0
	v_pk_mul_f32 v[130:131], s[22:23], v[130:131]
	v_pk_mul_f32 v[132:133], s[22:23], v[132:133]
	v_cvt_pk_bf16_f32 v130, v130, v131
	v_cvt_pk_bf16_f32 v131, v132, v133
	v_lshl_add_u64 v[132:133], v[142:143], 1, v[174:175]
	ds_write_b64 v249, v[130:131] offset:16
	ds_read_b128 v[130:133], v231 offset:64
	v_or_b32_e32 v160, 16, v156
	v_or_b32_e32 v144, v136, v160
	s_mov_b64 s[34:35], -1
	s_and_b64 vcc, exec, s[36:37]
	v_ashrrev_i32_e32 v145, 31, v144
	s_cbranch_vccnz .LBB0_967
	s_mov_b64 s[34:35], 0

.LBB0_969:
	s_nop 1
	v_pk_mul_f32 v[130:131], s[22:23], v[130:131]
	v_pk_mul_f32 v[132:133], s[22:23], v[132:133]
	v_cvt_pk_bf16_f32 v130, v130, v131
	v_cvt_pk_bf16_f32 v131, v132, v133
	v_lshl_add_u64 v[132:133], v[144:145], 1, v[174:175]
	ds_write_b64 v249, v[130:131] offset:32
	ds_read_b128 v[130:133], v231 offset:96
	v_or_b32_e32 v162, 24, v156
	v_or_b32_e32 v146, v136, v162
	s_mov_b64 s[34:35], -1
	s_and_b64 vcc, exec, s[36:37]
	v_ashrrev_i32_e32 v147, 31, v146
	s_cbranch_vccnz .LBB0_971
	s_mov_b64 s[34:35], 0

.LBB0_973:
	s_nop 1
	v_pk_mul_f32 v[130:131], s[22:23], v[130:131]
	v_pk_mul_f32 v[132:133], s[22:23], v[132:133]
	v_cvt_pk_bf16_f32 v130, v130, v131
	v_cvt_pk_bf16_f32 v131, v132, v133
	v_lshl_add_u64 v[132:133], v[146:147], 1, v[174:175]
	ds_write_b64 v249, v[130:131] offset:48
	ds_read_b128 v[130:133], v231 offset:128
	v_or_b32_e32 v164, 32, v156
	v_or_b32_e32 v148, v136, v164
	s_mov_b64 s[34:35], -1
	s_and_b64 vcc, exec, s[36:37]
	v_ashrrev_i32_e32 v149, 31, v148
	s_cbranch_vccnz .LBB0_975
	s_mov_b64 s[34:35], 0

.LBB0_977:
	s_nop 1
	v_pk_mul_f32 v[130:131], s[22:23], v[130:131]
	v_pk_mul_f32 v[132:133], s[22:23], v[132:133]
	v_cvt_pk_bf16_f32 v130, v130, v131
	v_cvt_pk_bf16_f32 v131, v132, v133
	v_lshl_add_u64 v[132:133], v[148:149], 1, v[174:175]
	ds_write_b64 v249, v[130:131] offset:64
	ds_read_b128 v[130:133], v231 offset:160
	v_or_b32_e32 v166, 40, v156
	v_or_b32_e32 v150, v136, v166
	s_mov_b64 s[34:35], -1
	s_and_b64 vcc, exec, s[36:37]
	v_ashrrev_i32_e32 v151, 31, v150
	s_cbranch_vccnz .LBB0_979
	s_mov_b64 s[34:35], 0

.LBB0_981:
	s_nop 1
	v_pk_mul_f32 v[130:131], s[22:23], v[130:131]
	v_pk_mul_f32 v[132:133], s[22:23], v[132:133]
	v_cvt_pk_bf16_f32 v130, v130, v131
	v_cvt_pk_bf16_f32 v131, v132, v133
	v_lshl_add_u64 v[132:133], v[150:151], 1, v[174:175]
	ds_write_b64 v249, v[130:131] offset:80
	ds_read_b128 v[130:133], v231 offset:192
	v_or_b32_e32 v168, 48, v156
	v_or_b32_e32 v152, v136, v168
	s_mov_b64 s[34:35], -1
	s_and_b64 vcc, exec, s[36:37]
	v_ashrrev_i32_e32 v153, 31, v152
	s_cbranch_vccnz .LBB0_983
	s_mov_b64 s[34:35], 0

.LBB0_985:
	s_nop 1
	v_pk_mul_f32 v[130:131], s[22:23], v[130:131]
	v_pk_mul_f32 v[132:133], s[22:23], v[132:133]
	v_cvt_pk_bf16_f32 v130, v130, v131
	v_cvt_pk_bf16_f32 v131, v132, v133
	v_lshl_add_u64 v[132:133], v[152:153], 1, v[174:175]
	ds_write_b64 v249, v[130:131] offset:96
	ds_read_b128 v[130:133], v231 offset:224
	v_or_b32_e32 v176, 56, v156
	v_or_b32_e32 v154, v136, v176
	s_mov_b64 s[34:35], -1
	s_and_b64 vcc, exec, s[36:37]
	v_ashrrev_i32_e32 v155, 31, v154
	s_cbranch_vccnz .LBB0_987
	s_mov_b64 s[34:35], 0

.LBB0_989:
	v_mul_f32_e32 v137, v51, v51
	v_fmac_f32_e32 v137, v50, v50
	v_fmac_f32_e32 v137, v52, v52
	v_fmac_f32_e32 v137, v53, v53
	v_fmac_f32_e32 v137, v54, v54
	v_fmac_f32_e32 v137, v55, v55
	v_fmac_f32_e32 v137, v56, v56
	v_fmac_f32_e32 v137, v57, v57
	v_fmac_f32_e32 v137, v58, v58
	v_fmac_f32_e32 v137, v59, v59
	v_fmac_f32_e32 v137, v60, v60
	v_fmac_f32_e32 v137, v61, v61
	v_fmac_f32_e32 v137, v62, v62
	v_fmac_f32_e32 v137, v63, v63
	v_fmac_f32_e32 v137, v64, v64
	v_fmac_f32_e32 v137, v65, v65
	v_fmac_f32_e32 v137, v18, v18
	v_fmac_f32_e32 v137, v19, v19
	v_fmac_f32_e32 v137, v20, v20
	v_fmac_f32_e32 v137, v21, v21
	v_fmac_f32_e32 v137, v22, v22
	v_fmac_f32_e32 v137, v23, v23
	v_pk_mul_f32 v[206:207], v[24:25], v[24:25]
	v_pk_mul_f32 v[204:205], v[26:27], v[26:27]
	v_add_f32_e32 v137, v206, v137
	v_add_f32_e32 v137, v207, v137
	v_add_f32_e32 v137, v204, v137
	v_pk_mul_f32 v[130:131], s[22:23], v[130:131]
	v_pk_mul_f32 v[132:133], s[22:23], v[132:133]
	v_pk_mul_f32 v[180:181], v[28:29], v[28:29]
	v_add_f32_e32 v137, v205, v137
	v_cvt_pk_bf16_f32 v130, v130, v131
	v_cvt_pk_bf16_f32 v131, v132, v133
	v_lshl_add_u64 v[132:133], v[154:155], 1, v[174:175]
	v_add_f32_e32 v137, v180, v137
	ds_write_b64 v249, v[130:131] offset:112
	s_waitcnt lgkmcnt(0)
	ds_read_b128 v[252:255], v250
	v_mov_b32_e32 v242, v251
	s_waitcnt lgkmcnt(0)
	global_store_dwordx4 v242, v[252:255], s[100:101]
	s_nop 1
	ds_read_b128 v[252:255], v250 offset:1152
	v_add_u32_e32 v242, 0x2000, v242
	s_waitcnt lgkmcnt(0)
	global_store_dwordx4 v242, v[252:255], s[100:101]
	s_nop 1
	ds_read_b128 v[252:255], v250 offset:2304
	v_add_u32_e32 v242, 0x2000, v242
	s_waitcnt lgkmcnt(0)
	global_store_dwordx4 v242, v[252:255], s[100:101]
	s_nop 1
	ds_read_b128 v[252:255], v250 offset:3456
	v_add_u32_e32 v242, 0x2000, v242
	s_waitcnt lgkmcnt(0)
	global_store_dwordx4 v242, v[252:255], s[100:101]
	s_nop 1
	v_pk_mul_f32 v[132:133], v[30:31], v[30:31]
	v_add_f32_e32 v137, v181, v137
	v_add_f32_e32 v132, v132, v137
	v_pk_mul_f32 v[130:131], v[32:33], v[32:33]
	v_add_f32_e32 v132, v133, v132
	v_add_f32_e32 v130, v130, v132
	v_add_f32_e32 v130, v131, v130
	ds_bpermute_b32 v131, v135, v130
	v_or_b32_e32 v171, 64, v136
	s_mov_b32 s4, 0x800000
	v_or_b32_e32 v136, v171, v156
	s_mov_b64 s[34:35], -1
	s_waitcnt lgkmcnt(0)
	v_add_f32_e32 v130, v130, v131
	v_fmamk_f32 v157, v130, 0x3c800000, v188
	ds_read_b128 v[130:133], v231
	v_cmp_gt_f32_e64 s[38:39], s4, v157
	s_and_b64 vcc, exec, s[36:37]
	v_ashrrev_i32_e32 v137, 31, v136
	s_cbranch_vccnz .LBB0_991
	s_mov_b64 s[34:35], 0

.LBB0_993:
	s_nop 1
	v_pk_mul_f32 v[130:131], s[22:23], v[130:131]
	v_pk_mul_f32 v[132:133], s[22:23], v[132:133]
	v_cvt_pk_bf16_f32 v130, v130, v131
	v_cvt_pk_bf16_f32 v131, v132, v133
	v_lshl_add_u64 v[132:133], v[136:137], 1, v[174:175]
	s_nop 1
	v_readfirstlane_b32 s100, v132
	v_readfirstlane_b32 s101, v133
	ds_write_b64 v249, v[130:131]
	ds_read_b128 v[130:133], v231 offset:32
	v_or_b32_e32 v156, v171, v158
	s_mov_b64 s[34:35], -1
	s_and_b64 vcc, exec, s[36:37]
	v_ashrrev_i32_e32 v157, 31, v156
	s_cbranch_vccnz .LBB0_995
	s_mov_b64 s[34:35], 0

.LBB0_997:
	s_nop 1
	v_pk_mul_f32 v[130:131], s[22:23], v[130:131]
	v_pk_mul_f32 v[132:133], s[22:23], v[132:133]
	v_cvt_pk_bf16_f32 v130, v130, v131
	v_cvt_pk_bf16_f32 v131, v132, v133
	v_lshl_add_u64 v[132:133], v[156:157], 1, v[174:175]
	ds_write_b64 v249, v[130:131] offset:16
	ds_read_b128 v[130:133], v231 offset:64
	v_or_b32_e32 v158, v171, v160
	s_mov_b64 s[34:35], -1
	s_and_b64 vcc, exec, s[36:37]
	v_ashrrev_i32_e32 v159, 31, v158
	s_cbranch_vccnz .LBB0_999
	s_mov_b64 s[34:35], 0

.LBB0_1001:
	s_nop 1
	v_pk_mul_f32 v[130:131], s[22:23], v[130:131]
	v_pk_mul_f32 v[132:133], s[22:23], v[132:133]
	v_cvt_pk_bf16_f32 v130, v130, v131
	v_cvt_pk_bf16_f32 v131, v132, v133
	v_lshl_add_u64 v[132:133], v[158:159], 1, v[174:175]
	ds_write_b64 v249, v[130:131] offset:32
	ds_read_b128 v[130:133], v231 offset:96
	v_or_b32_e32 v160, v171, v162
	s_mov_b64 s[34:35], -1
	s_and_b64 vcc, exec, s[36:37]
	v_ashrrev_i32_e32 v161, 31, v160
	s_cbranch_vccnz .LBB0_1003
	s_mov_b64 s[34:35], 0

.LBB0_1005:
	s_nop 1
	v_pk_mul_f32 v[130:131], s[22:23], v[130:131]
	v_pk_mul_f32 v[132:133], s[22:23], v[132:133]
	v_cvt_pk_bf16_f32 v130, v130, v131
	v_cvt_pk_bf16_f32 v131, v132, v133
	v_lshl_add_u64 v[132:133], v[160:161], 1, v[174:175]
	ds_write_b64 v249, v[130:131] offset:48
	ds_read_b128 v[130:133], v231 offset:128
	v_or_b32_e32 v162, v171, v164
	s_mov_b64 s[34:35], -1
	s_and_b64 vcc, exec, s[36:37]
	v_ashrrev_i32_e32 v163, 31, v162
	s_cbranch_vccnz .LBB0_1007
	s_mov_b64 s[34:35], 0

.LBB0_1009:
	s_nop 1
	v_pk_mul_f32 v[130:131], s[22:23], v[130:131]
	v_pk_mul_f32 v[132:133], s[22:23], v[132:133]
	v_cvt_pk_bf16_f32 v130, v130, v131
	v_cvt_pk_bf16_f32 v131, v132, v133
	v_lshl_add_u64 v[132:133], v[162:163], 1, v[174:175]
	ds_write_b64 v249, v[130:131] offset:64
	ds_read_b128 v[130:133], v231 offset:160
	v_or_b32_e32 v164, v171, v166
	s_mov_b64 s[34:35], -1
	s_and_b64 vcc, exec, s[36:37]
	v_ashrrev_i32_e32 v165, 31, v164
	s_cbranch_vccnz .LBB0_1011
	s_mov_b64 s[34:35], 0

.LBB0_1013:
	s_nop 1
	v_pk_mul_f32 v[130:131], s[22:23], v[130:131]
	v_pk_mul_f32 v[132:133], s[22:23], v[132:133]
	v_cvt_pk_bf16_f32 v130, v130, v131
	v_cvt_pk_bf16_f32 v131, v132, v133
	v_lshl_add_u64 v[132:133], v[164:165], 1, v[174:175]
	ds_write_b64 v249, v[130:131] offset:80
	ds_read_b128 v[130:133], v231 offset:192
	v_or_b32_e32 v166, v171, v168
	s_mov_b64 s[34:35], -1
	s_and_b64 vcc, exec, s[36:37]
	v_ashrrev_i32_e32 v167, 31, v166
	s_cbranch_vccnz .LBB0_1015
	s_mov_b64 s[34:35], 0

.LBB0_1017:
	s_nop 1
	v_pk_mul_f32 v[130:131], s[22:23], v[130:131]
	v_pk_mul_f32 v[132:133], s[22:23], v[132:133]
	v_cvt_pk_bf16_f32 v130, v130, v131
	v_cvt_pk_bf16_f32 v131, v132, v133
	v_lshl_add_u64 v[132:133], v[166:167], 1, v[174:175]
	ds_write_b64 v249, v[130:131] offset:96
	ds_read_b128 v[130:133], v231 offset:224
	v_or_b32_e32 v168, v171, v176
	s_mov_b64 s[34:35], -1
	s_and_b64 vcc, exec, s[36:37]
	v_ashrrev_i32_e32 v169, 31, v168
	s_cbranch_vccnz .LBB0_1019
	s_mov_b64 s[34:35], 0

.LBB0_1021:
	v_mul_f32_e32 v203, v99, v99
	v_fmac_f32_e32 v203, v98, v98
	v_fmac_f32_e32 v203, v100, v100
	v_fmac_f32_e32 v203, v101, v101
	v_fmac_f32_e32 v203, v102, v102
	v_fmac_f32_e32 v203, v103, v103
	v_fmac_f32_e32 v203, v104, v104
	v_fmac_f32_e32 v203, v105, v105
	v_fmac_f32_e32 v203, v106, v106
	v_fmac_f32_e32 v203, v107, v107
	v_fmac_f32_e32 v203, v108, v108
	v_fmac_f32_e32 v203, v109, v109
	v_fmac_f32_e32 v203, v110, v110
	v_fmac_f32_e32 v203, v111, v111
	v_fmac_f32_e32 v203, v112, v112
	v_fmac_f32_e32 v203, v113, v113
	v_fmac_f32_e32 v203, v66, v66
	v_fmac_f32_e32 v203, v67, v67
	v_fmac_f32_e32 v203, v68, v68
	v_fmac_f32_e32 v203, v69, v69
	v_fmac_f32_e32 v203, v70, v70
	v_fmac_f32_e32 v203, v71, v71
	v_pk_mul_f32 v[180:181], v[72:73], v[72:73]
	v_pk_mul_f32 v[176:177], v[74:75], v[74:75]
	v_add_f32_e32 v180, v180, v203
	v_add_f32_e32 v180, v181, v180
	v_pk_mul_f32 v[130:131], s[22:23], v[130:131]
	v_pk_mul_f32 v[132:133], s[22:23], v[132:133]
	v_add_f32_e32 v176, v176, v180
	v_cvt_pk_bf16_f32 v130, v130, v131
	v_cvt_pk_bf16_f32 v131, v132, v133
	v_lshl_add_u64 v[132:133], v[168:169], 1, v[174:175]
	v_pk_mul_f32 v[174:175], v[76:77], v[76:77]
	v_add_f32_e32 v176, v177, v176
	v_add_f32_e32 v174, v174, v176
	ds_write_b64 v249, v[130:131] offset:112
	s_waitcnt lgkmcnt(0)
	ds_read_b128 v[252:255], v250
	v_mov_b32_e32 v242, v251
	s_waitcnt lgkmcnt(0)
	global_store_dwordx4 v242, v[252:255], s[100:101]
	s_nop 1
	ds_read_b128 v[252:255], v250 offset:1152
	v_add_u32_e32 v242, 0x2000, v242
	s_waitcnt lgkmcnt(0)
	global_store_dwordx4 v242, v[252:255], s[100:101]
	s_nop 1
	ds_read_b128 v[252:255], v250 offset:2304
	v_add_u32_e32 v242, 0x2000, v242
	s_waitcnt lgkmcnt(0)
	global_store_dwordx4 v242, v[252:255], s[100:101]
	s_nop 1
	ds_read_b128 v[252:255], v250 offset:3456
	v_add_u32_e32 v242, 0x2000, v242
	s_waitcnt lgkmcnt(0)
	global_store_dwordx4 v242, v[252:255], s[100:101]
	s_nop 1
	v_pk_mul_f32 v[132:133], v[78:79], v[78:79]
	v_add_f32_e32 v174, v175, v174
	v_add_f32_e32 v132, v132, v174
	v_pk_mul_f32 v[130:131], v[80:81], v[80:81]
	v_add_f32_e32 v132, v133, v132
	v_add_f32_e32 v130, v130, v132
	v_add_f32_e32 v130, v131, v130
	ds_bpermute_b32 v131, v135, v130
	v_or_b32_e32 v172, 32, v170
	v_ashrrev_i32_e32 v173, 31, v172
	v_lshlrev_b64 v[170:171], 11, v[172:173]
	s_waitcnt lgkmcnt(0)
	v_add_f32_e32 v130, v130, v131
	v_fmamk_f32 v130, v130, 0x3c800000, v188
	v_cmp_gt_f32_e32 vcc, s4, v130
	v_mul_f32_e32 v131, 0x4b800000, v130
	s_nop 0
	v_cndmask_b32_e32 v130, v130, v131, vcc
	v_rsq_f32_e32 v130, v130
	s_nop 0
	v_mul_f32_e32 v131, 0x45800000, v130
	v_cndmask_b32_e32 v174, v130, v131, vcc
	ds_read_b128 v[130:133], v231
	v_pk_mul_f32 v[176:177], v[98:99], v[174:175] op_sel_hi:[1,0]
	s_andn2_b64 vcc, exec, s[0:1]
	s_waitcnt vmcnt(8) lgkmcnt(0)
	v_pk_mul_f32 v[130:131], v[130:131], v[176:177]
	v_pk_mul_f32 v[176:177], v[100:101], v[174:175] op_sel_hi:[1,0]
	v_cndmask_b32_e64 v175, 0, 1, s[0:1]
	v_readlane_b32 s0, v246, 44
	v_readlane_b32 s1, v246, 45
	v_pk_mul_f32 v[132:133], v[132:133], v[176:177]
	v_cmp_ne_u32_e64 s[36:37], 1, v175
	v_lshl_add_u64 v[170:171], s[0:1], 0, v[170:171]
	s_cbranch_vccnz .LBB0_1023
	v_lshl_add_u64 v[176:177], v[140:141], 2, v[170:171]
	global_store_dwordx4 v[176:177], v[130:133], off
.LBB0_1023:
	v_lshlrev_b64 v[172:173], 10, v[172:173]
	v_lshl_add_u64 v[172:173], s[28:29], 0, v[172:173]
	v_pk_mul_f32 v[130:131], s[22:23], v[130:131]
	v_pk_mul_f32 v[132:133], s[22:23], v[132:133]
	v_cvt_pk_bf16_f32 v130, v130, v131
	v_cvt_pk_bf16_f32 v131, v132, v133
	v_lshl_add_u64 v[132:133], v[140:141], 1, v[172:173]
	s_nop 1
	v_readfirstlane_b32 s100, v132
	v_readfirstlane_b32 s101, v133
	ds_write_b64 v249, v[130:131]
	ds_read_b128 v[130:133], v231 offset:32
	v_mov_b32_e32 v175, v174
	v_pk_mul_f32 v[140:141], v[102:103], v[174:175]
	s_and_b64 vcc, exec, s[36:37]
	s_waitcnt vmcnt(8) lgkmcnt(0)
	v_pk_mul_f32 v[130:131], v[140:141], v[130:131]
	v_pk_mul_f32 v[140:141], v[104:105], v[174:175]
	s_nop 0
	v_pk_mul_f32 v[132:133], v[140:141], v[132:133]
	s_cbranch_vccnz .LBB0_1025
	v_lshl_add_u64 v[140:141], v[142:143], 2, v[170:171]
	global_store_dwordx4 v[140:141], v[130:133], off
.LBB0_1025:
	s_nop 1
	v_pk_mul_f32 v[130:131], s[22:23], v[130:131]
	v_pk_mul_f32 v[132:133], s[22:23], v[132:133]
	v_cvt_pk_bf16_f32 v130, v130, v131
	v_cvt_pk_bf16_f32 v131, v132, v133
	v_lshl_add_u64 v[132:133], v[142:143], 1, v[172:173]
	ds_write_b64 v249, v[130:131] offset:16
	ds_read_b128 v[130:133], v231 offset:64
	v_pk_mul_f32 v[140:141], v[106:107], v[174:175]
	s_and_b64 vcc, exec, s[36:37]
	s_mov_b32 s0, 0x800000
	s_waitcnt vmcnt(8) lgkmcnt(0)
	v_pk_mul_f32 v[130:131], v[140:141], v[130:131]
	v_pk_mul_f32 v[140:141], v[108:109], v[174:175]
	s_nop 0
	v_pk_mul_f32 v[132:133], v[140:141], v[132:133]
	s_cbranch_vccnz .LBB0_1027
	v_lshl_add_u64 v[140:141], v[144:145], 2, v[170:171]
	global_store_dwordx4 v[140:141], v[130:133], off
.LBB0_1027:
	s_nop 1
	v_pk_mul_f32 v[130:131], s[22:23], v[130:131]
	v_pk_mul_f32 v[132:133], s[22:23], v[132:133]
	v_cvt_pk_bf16_f32 v130, v130, v131
	v_cvt_pk_bf16_f32 v131, v132, v133
	v_lshl_add_u64 v[132:133], v[144:145], 1, v[172:173]
	ds_write_b64 v249, v[130:131] offset:32
	ds_read_b128 v[130:133], v231 offset:96
	v_pk_mul_f32 v[140:141], v[110:111], v[174:175]
	s_and_b64 vcc, exec, s[36:37]
	s_waitcnt vmcnt(8) lgkmcnt(0)
	v_pk_mul_f32 v[130:131], v[140:141], v[130:131]
	v_pk_mul_f32 v[140:141], v[112:113], v[174:175]
	s_nop 0
	v_pk_mul_f32 v[132:133], v[140:141], v[132:133]
	s_cbranch_vccnz .LBB0_1029
	v_lshl_add_u64 v[140:141], v[146:147], 2, v[170:171]
	global_store_dwordx4 v[140:141], v[130:133], off
.LBB0_1029:
	s_nop 1
	v_pk_mul_f32 v[130:131], s[22:23], v[130:131]
	v_pk_mul_f32 v[132:133], s[22:23], v[132:133]
	v_cvt_pk_bf16_f32 v130, v130, v131
	v_cvt_pk_bf16_f32 v131, v132, v133
	v_lshl_add_u64 v[132:133], v[146:147], 1, v[172:173]
	ds_write_b64 v249, v[130:131] offset:48
	ds_read_b128 v[130:133], v231 offset:128
	v_pk_mul_f32 v[140:141], v[66:67], v[174:175]
	s_and_b64 vcc, exec, s[36:37]
	s_waitcnt vmcnt(8) lgkmcnt(0)
	v_pk_mul_f32 v[130:131], v[140:141], v[130:131]
	v_pk_mul_f32 v[140:141], v[68:69], v[174:175]
	s_nop 0
	v_pk_mul_f32 v[132:133], v[140:141], v[132:133]
	s_cbranch_vccnz .LBB0_1031
	v_lshl_add_u64 v[140:141], v[148:149], 2, v[170:171]
	global_store_dwordx4 v[140:141], v[130:133], off
.LBB0_1031:
	s_nop 1
	v_pk_mul_f32 v[130:131], s[22:23], v[130:131]
	v_pk_mul_f32 v[132:133], s[22:23], v[132:133]
	v_cvt_pk_bf16_f32 v130, v130, v131
	v_cvt_pk_bf16_f32 v131, v132, v133
	v_lshl_add_u64 v[132:133], v[148:149], 1, v[172:173]
	ds_write_b64 v249, v[130:131] offset:64
	ds_read_b128 v[130:133], v231 offset:160
	v_pk_mul_f32 v[140:141], v[70:71], v[174:175]
	s_and_b64 vcc, exec, s[36:37]
	s_waitcnt vmcnt(8) lgkmcnt(0)
	v_pk_mul_f32 v[130:131], v[140:141], v[130:131]
	v_pk_mul_f32 v[140:141], v[72:73], v[174:175]
	s_nop 0
	v_pk_mul_f32 v[132:133], v[140:141], v[132:133]
	s_cbranch_vccnz .LBB0_1033
	v_lshl_add_u64 v[140:141], v[150:151], 2, v[170:171]
	global_store_dwordx4 v[140:141], v[130:133], off
.LBB0_1033:
	s_nop 1
	v_pk_mul_f32 v[130:131], s[22:23], v[130:131]
	v_pk_mul_f32 v[132:133], s[22:23], v[132:133]
	v_cvt_pk_bf16_f32 v130, v130, v131
	v_cvt_pk_bf16_f32 v131, v132, v133
	v_lshl_add_u64 v[132:133], v[150:151], 1, v[172:173]
	ds_write_b64 v249, v[130:131] offset:80
	ds_read_b128 v[130:133], v231 offset:192
	v_pk_mul_f32 v[140:141], v[74:75], v[174:175]
	s_and_b64 vcc, exec, s[36:37]
	s_waitcnt vmcnt(8) lgkmcnt(0)
	v_pk_mul_f32 v[130:131], v[140:141], v[130:131]
	v_pk_mul_f32 v[140:141], v[76:77], v[174:175]
	s_nop 0
	v_pk_mul_f32 v[132:133], v[140:141], v[132:133]
	s_cbranch_vccnz .LBB0_1035
	v_lshl_add_u64 v[140:141], v[152:153], 2, v[170:171]
	global_store_dwordx4 v[140:141], v[130:133], off
.LBB0_1035:
	s_nop 1
	v_pk_mul_f32 v[130:131], s[22:23], v[130:131]
	v_pk_mul_f32 v[132:133], s[22:23], v[132:133]
	v_cvt_pk_bf16_f32 v130, v130, v131
	v_cvt_pk_bf16_f32 v131, v132, v133
	v_lshl_add_u64 v[132:133], v[152:153], 1, v[172:173]
	ds_write_b64 v249, v[130:131] offset:96
	ds_read_b128 v[130:133], v231 offset:224
	v_pk_mul_f32 v[140:141], v[78:79], v[174:175]
	v_pk_mul_f32 v[142:143], v[80:81], v[174:175]
	s_and_b64 vcc, exec, s[36:37]
	s_waitcnt vmcnt(8) lgkmcnt(0)
	v_pk_mul_f32 v[130:131], v[140:141], v[130:131]
	v_pk_mul_f32 v[132:133], v[142:143], v[132:133]
	s_cbranch_vccnz .LBB0_1037
	v_lshl_add_u64 v[140:141], v[154:155], 2, v[170:171]
	global_store_dwordx4 v[140:141], v[130:133], off
.LBB0_1037:
	v_mul_f32_e32 v146, v35, v35
	v_fmac_f32_e32 v146, v34, v34
	v_fmac_f32_e32 v146, v36, v36
	v_fmac_f32_e32 v146, v37, v37
	v_fmac_f32_e32 v146, v38, v38
	v_fmac_f32_e32 v146, v39, v39
	v_fmac_f32_e32 v146, v40, v40
	v_fmac_f32_e32 v146, v41, v41
	v_fmac_f32_e32 v146, v42, v42
	v_fmac_f32_e32 v146, v43, v43
	v_fmac_f32_e32 v146, v44, v44
	v_fmac_f32_e32 v146, v45, v45
	v_fmac_f32_e32 v146, v46, v46
	v_fmac_f32_e32 v146, v47, v47
	v_fmac_f32_e32 v146, v48, v48
	v_fmac_f32_e32 v146, v49, v49
	v_fmac_f32_e32 v146, v2, v2
	v_fmac_f32_e32 v146, v3, v3
	v_fmac_f32_e32 v146, v4, v4
	v_fmac_f32_e32 v146, v5, v5
	v_fmac_f32_e32 v146, v6, v6
	v_fmac_f32_e32 v146, v7, v7
	v_pk_mul_f32 v[144:145], v[8:9], v[8:9]
	v_pk_mul_f32 v[142:143], v[10:11], v[10:11]
	v_add_f32_e32 v144, v144, v146
	v_add_f32_e32 v144, v145, v144
	v_add_f32_e32 v142, v142, v144
	v_pk_mul_f32 v[130:131], s[22:23], v[130:131]
	v_pk_mul_f32 v[132:133], s[22:23], v[132:133]
	v_pk_mul_f32 v[140:141], v[12:13], v[12:13]
	v_add_f32_e32 v142, v143, v142
	v_cvt_pk_bf16_f32 v130, v130, v131
	v_cvt_pk_bf16_f32 v131, v132, v133
	v_lshl_add_u64 v[132:133], v[154:155], 1, v[172:173]
	v_add_f32_e32 v140, v140, v142
	ds_write_b64 v249, v[130:131] offset:112
	s_waitcnt lgkmcnt(0)
	ds_read_b128 v[252:255], v250
	v_mov_b32_e32 v242, v251
	s_waitcnt lgkmcnt(0)
	global_store_dwordx4 v242, v[252:255], s[100:101]
	s_nop 1
	ds_read_b128 v[252:255], v250 offset:1152
	v_add_u32_e32 v242, 0x2000, v242
	s_waitcnt lgkmcnt(0)
	global_store_dwordx4 v242, v[252:255], s[100:101]
	s_nop 1
	ds_read_b128 v[252:255], v250 offset:2304
	v_add_u32_e32 v242, 0x2000, v242
	s_waitcnt lgkmcnt(0)
	global_store_dwordx4 v242, v[252:255], s[100:101]
	s_nop 1
	ds_read_b128 v[252:255], v250 offset:3456
	v_add_u32_e32 v242, 0x2000, v242
	s_waitcnt lgkmcnt(0)
	global_store_dwordx4 v242, v[252:255], s[100:101]
	s_nop 1
	v_pk_mul_f32 v[132:133], v[14:15], v[14:15]
	v_add_f32_e32 v140, v141, v140
	v_add_f32_e32 v132, v132, v140
	v_pk_mul_f32 v[130:131], v[16:17], v[16:17]
	v_add_f32_e32 v132, v133, v132
	v_add_f32_e32 v130, v130, v132
	v_add_f32_e32 v130, v131, v130
	ds_bpermute_b32 v131, v135, v130
	s_waitcnt lgkmcnt(0)
	v_add_f32_e32 v130, v130, v131
	v_fmamk_f32 v130, v130, 0x3c800000, v188
	v_cmp_gt_f32_e32 vcc, s0, v130
	v_mul_f32_e32 v131, 0x4b800000, v130
	s_nop 0
	v_cndmask_b32_e32 v130, v130, v131, vcc
	v_rsq_f32_e32 v130, v130
	s_nop 0
	v_mul_f32_e32 v131, 0x45800000, v130
	v_cndmask_b32_e32 v140, v130, v131, vcc
	ds_read_b128 v[130:133], v231
	v_pk_mul_f32 v[142:143], v[34:35], v[140:141] op_sel_hi:[1,0]
	s_and_b64 vcc, exec, s[36:37]
	s_waitcnt vmcnt(8) lgkmcnt(0)
	v_pk_mul_f32 v[130:131], v[130:131], v[142:143]
	v_pk_mul_f32 v[142:143], v[36:37], v[140:141] op_sel_hi:[1,0]
	s_nop 0
	v_pk_mul_f32 v[132:133], v[132:133], v[142:143]
	s_cbranch_vccnz .LBB0_1039
	v_lshl_add_u64 v[142:143], v[136:137], 2, v[170:171]
	global_store_dwordx4 v[142:143], v[130:133], off
.LBB0_1039:
	s_nop 1
	v_pk_mul_f32 v[130:131], s[22:23], v[130:131]
	v_pk_mul_f32 v[132:133], s[22:23], v[132:133]
	v_cvt_pk_bf16_f32 v130, v130, v131
	v_cvt_pk_bf16_f32 v131, v132, v133
	v_lshl_add_u64 v[132:133], v[136:137], 1, v[172:173]
	s_nop 1
	v_readfirstlane_b32 s100, v132
	v_readfirstlane_b32 s101, v133
	ds_write_b64 v249, v[130:131]
	ds_read_b128 v[130:133], v231 offset:32
	v_mov_b32_e32 v141, v140
	v_pk_mul_f32 v[136:137], v[38:39], v[140:141]
	s_and_b64 vcc, exec, s[36:37]
	s_waitcnt vmcnt(8) lgkmcnt(0)
	v_pk_mul_f32 v[130:131], v[136:137], v[130:131]
	v_pk_mul_f32 v[136:137], v[40:41], v[140:141]
	s_nop 0
	v_pk_mul_f32 v[132:133], v[136:137], v[132:133]
	s_cbranch_vccnz .LBB0_1041
	v_lshl_add_u64 v[136:137], v[156:157], 2, v[170:171]
	global_store_dwordx4 v[136:137], v[130:133], off
.LBB0_1041:
	s_nop 1
	v_pk_mul_f32 v[130:131], s[22:23], v[130:131]
	v_pk_mul_f32 v[132:133], s[22:23], v[132:133]
	v_cvt_pk_bf16_f32 v130, v130, v131
	v_cvt_pk_bf16_f32 v131, v132, v133
	v_lshl_add_u64 v[132:133], v[156:157], 1, v[172:173]
	ds_write_b64 v249, v[130:131] offset:16
	ds_read_b128 v[130:133], v231 offset:64
	v_pk_mul_f32 v[136:137], v[42:43], v[140:141]
	s_and_b64 vcc, exec, s[36:37]
	s_waitcnt vmcnt(8) lgkmcnt(0)
	v_pk_mul_f32 v[130:131], v[136:137], v[130:131]
	v_pk_mul_f32 v[136:137], v[44:45], v[140:141]
	s_nop 0
	v_pk_mul_f32 v[132:133], v[136:137], v[132:133]
	s_cbranch_vccnz .LBB0_1043
	v_lshl_add_u64 v[136:137], v[158:159], 2, v[170:171]
	global_store_dwordx4 v[136:137], v[130:133], off
.LBB0_1043:
	s_nop 1
	v_pk_mul_f32 v[130:131], s[22:23], v[130:131]
	v_pk_mul_f32 v[132:133], s[22:23], v[132:133]
	v_cvt_pk_bf16_f32 v130, v130, v131
	v_cvt_pk_bf16_f32 v131, v132, v133
	v_lshl_add_u64 v[132:133], v[158:159], 1, v[172:173]
	ds_write_b64 v249, v[130:131] offset:32
	ds_read_b128 v[130:133], v231 offset:96
	v_pk_mul_f32 v[136:137], v[46:47], v[140:141]
	s_and_b64 vcc, exec, s[36:37]
	s_waitcnt vmcnt(8) lgkmcnt(0)
	v_pk_mul_f32 v[130:131], v[136:137], v[130:131]
	v_pk_mul_f32 v[136:137], v[48:49], v[140:141]
	s_nop 0
	v_pk_mul_f32 v[132:133], v[136:137], v[132:133]
	s_cbranch_vccnz .LBB0_1045
	v_lshl_add_u64 v[136:137], v[160:161], 2, v[170:171]
	global_store_dwordx4 v[136:137], v[130:133], off
.LBB0_1045:
	s_nop 1
	v_pk_mul_f32 v[130:131], s[22:23], v[130:131]
	v_pk_mul_f32 v[132:133], s[22:23], v[132:133]
	v_cvt_pk_bf16_f32 v130, v130, v131
	v_cvt_pk_bf16_f32 v131, v132, v133
	v_lshl_add_u64 v[132:133], v[160:161], 1, v[172:173]
	ds_write_b64 v249, v[130:131] offset:48
	ds_read_b128 v[130:133], v231 offset:128
	v_pk_mul_f32 v[136:137], v[2:3], v[140:141]
	s_and_b64 vcc, exec, s[36:37]
	s_waitcnt vmcnt(8) lgkmcnt(0)
	v_pk_mul_f32 v[130:131], v[136:137], v[130:131]
	v_pk_mul_f32 v[136:137], v[4:5], v[140:141]
	s_nop 0
	v_pk_mul_f32 v[132:133], v[136:137], v[132:133]
	s_cbranch_vccnz .LBB0_1047
	v_lshl_add_u64 v[136:137], v[162:163], 2, v[170:171]
	global_store_dwordx4 v[136:137], v[130:133], off
.LBB0_1047:
	s_nop 1
	v_pk_mul_f32 v[130:131], s[22:23], v[130:131]
	v_pk_mul_f32 v[132:133], s[22:23], v[132:133]
	v_cvt_pk_bf16_f32 v130, v130, v131
	v_cvt_pk_bf16_f32 v131, v132, v133
	v_lshl_add_u64 v[132:133], v[162:163], 1, v[172:173]
	ds_write_b64 v249, v[130:131] offset:64
	ds_read_b128 v[130:133], v231 offset:160
	v_pk_mul_f32 v[136:137], v[6:7], v[140:141]
	s_and_b64 vcc, exec, s[36:37]
	s_waitcnt vmcnt(8) lgkmcnt(0)
	v_pk_mul_f32 v[130:131], v[136:137], v[130:131]
	v_pk_mul_f32 v[136:137], v[8:9], v[140:141]
	s_nop 0
	v_pk_mul_f32 v[132:133], v[136:137], v[132:133]
	s_cbranch_vccnz .LBB0_1049
	v_lshl_add_u64 v[136:137], v[164:165], 2, v[170:171]
	global_store_dwordx4 v[136:137], v[130:133], off
.LBB0_1049:
	s_nop 1
	v_pk_mul_f32 v[130:131], s[22:23], v[130:131]
	v_pk_mul_f32 v[132:133], s[22:23], v[132:133]
	v_cvt_pk_bf16_f32 v130, v130, v131
	v_cvt_pk_bf16_f32 v131, v132, v133
	v_lshl_add_u64 v[132:133], v[164:165], 1, v[172:173]
	ds_write_b64 v249, v[130:131] offset:80
	ds_read_b128 v[130:133], v231 offset:192
	v_pk_mul_f32 v[136:137], v[10:11], v[140:141]
	s_and_b64 vcc, exec, s[36:37]
	s_waitcnt vmcnt(8) lgkmcnt(0)
	v_pk_mul_f32 v[130:131], v[136:137], v[130:131]
	v_pk_mul_f32 v[136:137], v[12:13], v[140:141]
	s_nop 0
	v_pk_mul_f32 v[132:133], v[136:137], v[132:133]
	s_cbranch_vccnz .LBB0_1051
	v_lshl_add_u64 v[136:137], v[166:167], 2, v[170:171]
	global_store_dwordx4 v[136:137], v[130:133], off
.LBB0_1051:
	s_nop 1
	v_pk_mul_f32 v[130:131], s[22:23], v[130:131]
	v_pk_mul_f32 v[132:133], s[22:23], v[132:133]
	v_cvt_pk_bf16_f32 v130, v130, v131
	v_cvt_pk_bf16_f32 v131, v132, v133
	v_lshl_add_u64 v[132:133], v[166:167], 1, v[172:173]
	ds_write_b64 v249, v[130:131] offset:96
	ds_read_b128 v[130:133], v231 offset:224
	v_pk_mul_f32 v[136:137], v[14:15], v[140:141]
	v_pk_mul_f32 v[138:139], v[16:17], v[140:141]
	s_and_b64 vcc, exec, s[36:37]
	s_waitcnt vmcnt(8) lgkmcnt(0)
	v_pk_mul_f32 v[130:131], v[136:137], v[130:131]
	v_pk_mul_f32 v[132:133], v[138:139], v[132:133]
	s_cbranch_vccnz .LBB0_1053
	v_lshl_add_u64 v[136:137], v[168:169], 2, v[170:171]
	global_store_dwordx4 v[136:137], v[130:133], off
.LBB0_1053:
	s_nop 1
	v_pk_mul_f32 v[130:131], s[22:23], v[130:131]
	v_pk_mul_f32 v[132:133], s[22:23], v[132:133]
	v_cvt_pk_bf16_f32 v130, v130, v131
	v_cvt_pk_bf16_f32 v131, v132, v133
	v_lshl_add_u64 v[132:133], v[168:169], 1, v[172:173]
	ds_write_b64 v249, v[130:131] offset:112
	s_waitcnt lgkmcnt(0)
	ds_read_b128 v[252:255], v250
	v_mov_b32_e32 v242, v251
	s_waitcnt lgkmcnt(0)
	global_store_dwordx4 v242, v[252:255], s[100:101]
	s_nop 1
	ds_read_b128 v[252:255], v250 offset:1152
	v_add_u32_e32 v242, 0x2000, v242
	s_waitcnt lgkmcnt(0)
	global_store_dwordx4 v242, v[252:255], s[100:101]
	s_nop 1
	ds_read_b128 v[252:255], v250 offset:2304
	v_add_u32_e32 v242, 0x2000, v242
	s_waitcnt lgkmcnt(0)
	global_store_dwordx4 v242, v[252:255], s[100:101]
	s_nop 1
	ds_read_b128 v[252:255], v250 offset:3456
	v_add_u32_e32 v242, 0x2000, v242
	s_waitcnt lgkmcnt(0)
	global_store_dwordx4 v242, v[252:255], s[100:101]
	s_nop 1
